# hyena prompt item: the 22 neighbour loads of the two short convolutions issued up front instead of one load+wait per tap
# speedup vs baseline: 1.0002x; 1.0002x over previous
.LBB0_435:
	s_or_b64 exec, exec, s[0:1]
	v_ashrrev_i32_e32 v24, 1, v10
	v_bitop3_b32 v0, v10, 7, v10 bitop3:0xc
	v_and_b32_e32 v15, 0xffffffe0, v24
	v_or_b32_e32 v16, v15, v0
	s_movk_i32 s0, 0x420
	v_bitop3_b32 v26, v10, 15, v10 bitop3:0xc
	v_bfe_u32 v14, v10, 4, 2
	v_mad_u32_u24 v25, v0, s0, v205
	v_sub_u32_e32 v0, v26, v16
	v_lshlrev_b32_e32 v0, 1, v0
	v_lshlrev_b32_e32 v27, 4, v14
	v_add3_u32 v17, v25, v0, v27
	s_waitcnt lgkmcnt(0)
	s_barrier
	ds_read_b128 v[2:5], v17 offset:29408
	v_and_b32_e32 v29, 15, v10
	s_movk_i32 s0, 0x210
	v_mad_u32_u24 v19, v29, s0, v205
	v_add_u32_e32 v18, v19, v27
	ds_read_b128 v[6:9], v18 offset:20480
	ds_read_b128 v[10:13], v17 offset:29472
	ds_read_b128 v[30:33], v18 offset:20544
	ds_read_b128 v[20:23], v17 offset:29536
	s_waitcnt lgkmcnt(3)
	v_mfma_f32_16x16x32_bf16 v[2:5], v[2:5], v[6:9], 0
	v_readlane_b32 s0, v251, 39
	v_lshlrev_b32_e32 v0, 10, v29
	v_readlane_b32 s1, v251, 40
	s_waitcnt lgkmcnt(1)
	v_mfma_f32_16x16x32_bf16 v[2:5], v[10:13], v[30:33], v[2:5]
	ds_read_b128 v[34:37], v18 offset:20608
	ds_read_b128 v[10:13], v17 offset:29600
	s_or_b32 s26, s74, 0x100
	v_readlane_b32 s4, v250, 59
	s_waitcnt lgkmcnt(1)
	v_mfma_f32_16x16x32_bf16 v[2:5], v[20:23], v[34:37], v[2:5]
	ds_read_b128 v[38:41], v18 offset:20672
	ds_read_b128 v[20:23], v17 offset:29664
	ds_read_b128 v[42:45], v18 offset:20736
	v_readlane_b32 s14, v249, 5
	v_readlane_b32 s15, v249, 6
	s_waitcnt lgkmcnt(2)
	v_mfma_f32_16x16x32_bf16 v[2:5], v[10:13], v[38:41], v[2:5]
	ds_read_b128 v[10:13], v17 offset:29728
	v_readlane_b32 s5, v250, 60
	v_readlane_b32 s6, v250, 61
	s_waitcnt lgkmcnt(1)
	v_mfma_f32_16x16x32_bf16 v[2:5], v[20:23], v[42:45], v[2:5]
	ds_read_b128 v[46:49], v18 offset:20800
	ds_read_b128 v[20:23], v17 offset:29792
	ds_read_b128 v[50:53], v18 offset:20864
	ds_read_b128 v[54:57], v17 offset:29856
	ds_read_b128 v[58:61], v18 offset:20928
	v_readlane_b32 s7, v250, 62
	s_waitcnt lgkmcnt(4)
	v_mfma_f32_16x16x32_bf16 v[2:5], v[10:13], v[46:49], v[2:5]
	v_lshl_add_u64 v[12:13], s[0:1], 0, v[0:1]
	v_or_b32_e32 v0, 16, v16
	v_sub_u32_e32 v0, v26, v0
	s_waitcnt lgkmcnt(2)
	v_mfma_f32_16x16x32_bf16 v[2:5], v[20:23], v[50:53], v[2:5]
	v_lshlrev_b32_e32 v0, 1, v0
	s_add_u32 s0, s24, 0x400
	v_add3_u32 v16, v25, v0, v27
	s_addc_u32 s1, s25, 0
	v_lshl_or_b32 v10, v14, 2, v15
	s_waitcnt lgkmcnt(0)
	v_mfma_f32_16x16x32_bf16 v[2:5], v[54:57], v[58:61], v[2:5]
	ds_read_b128 v[54:57], v16 offset:29408
	global_load_dword v22, v1, s[24:25] offset:1024
	global_load_dword v23, v1, s[0:1] offset:3072
	global_load_dword v20, v202, s[24:25] offset:3072
	global_load_dword v0, v1, s[52:53] offset:1024
	v_mad_u64_u32 v[14:15], s[0:1], s26, v215, v[12:13]
	s_ashr_i32 s1, s23, 31
	s_add_u32 s0, s23, s29
	s_addc_u32 s1, s1, s61
	s_lshl_b64 s[0:1], s[0:1], 2
	v_ashrrev_i32_e32 v11, 31, v10
	s_add_u32 s54, s14, s0
	v_lshl_add_u64 v[14:15], v[10:11], 2, v[14:15]
	global_load_dword v28, v[14:15], off
	global_load_dword v100, v[14:15], off offset:-4
	global_load_dword v101, v[14:15], off offset:4
	global_load_dword v102, v[14:15], off offset:8
	global_load_dword v103, v[14:15], off offset:12
	global_load_dword v104, v[14:15], off offset:16
	global_load_dword v106, v[14:15], off offset:60
	global_load_dword v105, v[14:15], off offset:64
	global_load_dword v107, v[14:15], off offset:68
	global_load_dword v108, v[14:15], off offset:72
	global_load_dword v109, v[14:15], off offset:76
	global_load_dword v110, v[14:15], off offset:80
	s_addc_u32 s55, s15, s1
	global_load_dword v21, v1, s[54:55] offset:-3072
	s_waitcnt lgkmcnt(0)
	v_mfma_f32_16x16x32_bf16 v[6:9], v[54:57], v[6:9], 0
	ds_read_b128 v[54:57], v16 offset:29472
	v_cmp_lt_i32_e64 s[0:1], 0, v10
	v_readlane_b32 s8, v250, 63
	s_waitcnt lgkmcnt(0)
	v_mfma_f32_16x16x32_bf16 v[6:9], v[54:57], v[30:33], v[6:9]
	ds_read_b128 v[30:33], v16 offset:29536
	v_readlane_b32 s9, v249, 0
	v_readlane_b32 s10, v249, 1
	s_waitcnt lgkmcnt(0)
	v_mfma_f32_16x16x32_bf16 v[6:9], v[30:33], v[34:37], v[6:9]
	ds_read_b128 v[30:33], v16 offset:29600
	v_readlane_b32 s11, v249, 2
	v_readlane_b32 s12, v249, 3
	s_waitcnt lgkmcnt(0)
	v_mfma_f32_16x16x32_bf16 v[6:9], v[30:33], v[38:41], v[6:9]
	ds_read_b128 v[30:33], v16 offset:29664
	v_readlane_b32 s13, v249, 4
	v_readlane_b32 s16, v249, 7
	s_waitcnt lgkmcnt(0)
	v_mfma_f32_16x16x32_bf16 v[6:9], v[30:33], v[42:45], v[6:9]
	ds_read_b128 v[30:33], v16 offset:29728
	v_readlane_b32 s17, v249, 8
	v_readlane_b32 s18, v249, 9
	s_waitcnt lgkmcnt(0)
	v_mfma_f32_16x16x32_bf16 v[6:9], v[30:33], v[46:49], v[6:9]
	ds_read_b128 v[30:33], v16 offset:29792
	v_readlane_b32 s19, v249, 10
	s_waitcnt vmcnt(1)
	v_fma_f32 v25, v23, v28, v0
	s_waitcnt lgkmcnt(0)
	v_mfma_f32_16x16x32_bf16 v[6:9], v[30:33], v[50:53], v[6:9]
	ds_read_b128 v[30:33], v16 offset:29856
	s_waitcnt lgkmcnt(0)
	v_mfma_f32_16x16x32_bf16 v[6:9], v[30:33], v[58:61], v[6:9]
	s_and_saveexec_b64 s[36:37], s[0:1]
	s_cbranch_execz .LBB0_437
	v_mov_b32_e32 v26, v100
	s_waitcnt vmcnt(0)
	v_fmac_f32_e32 v25, v22, v26
.LBB0_437:
	s_or_b64 exec, exec, s[36:37]
	s_movk_i32 s4, 0xfe
	v_cmp_lt_i32_e64 s[36:37], s4, v10
	s_and_saveexec_b64 s[38:39], s[36:37]
	s_xor_b64 s[38:39], exec, s[38:39]
	s_cbranch_execz .LBB0_439
	v_mov_b32_e32 v31, v101
.LBB0_439:
	s_andn2_saveexec_b64 s[38:39], s[38:39]
	s_cbranch_execz .LBB0_441
	v_mov_b32_e32 v31, v101
	s_waitcnt vmcnt(0)
	v_fmac_f32_e32 v25, v20, v31
.LBB0_441:
	s_or_b64 exec, exec, s[38:39]
	v_mul_u32_u24_e32 v26, 0x1f0, v29
	v_lshlrev_b32_e32 v27, 2, v10
	v_add3_u32 v30, v19, v26, v27
	ds_read_b32 v26, v30
	s_waitcnt vmcnt(0)
	v_fma_f32 v27, v23, v31, v0
	v_cmp_lt_i32_e32 vcc, -1, v24
	s_and_saveexec_b64 s[38:39], vcc
	v_fmac_f32_e32 v27, v22, v28
	s_or_b64 exec, exec, s[38:39]
	v_or_b32_e32 v24, 1, v10
	v_cmp_lt_i32_e64 s[38:39], s4, v24
	s_and_saveexec_b64 s[40:41], s[38:39]
	s_xor_b64 s[40:41], exec, s[40:41]
	s_cbranch_execz .LBB0_445
	v_mov_b32_e32 v33, v102
.LBB0_445:
	s_andn2_saveexec_b64 s[40:41], s[40:41]
	s_cbranch_execz .LBB0_447
	v_mov_b32_e32 v33, v102
	s_waitcnt vmcnt(0)
	v_fmac_f32_e32 v27, v20, v33
.LBB0_447:
	s_or_b64 exec, exec, s[40:41]
	ds_read_b32 v24, v30 offset:4
	s_waitcnt vmcnt(0)
	v_fma_f32 v28, v23, v33, v0
	s_and_saveexec_b64 s[40:41], vcc
	v_fmac_f32_e32 v28, v22, v31
	s_or_b64 exec, exec, s[40:41]
	v_or_b32_e32 v31, 2, v10
	v_cmp_lt_i32_e64 s[40:41], s4, v31
	s_and_saveexec_b64 s[42:43], s[40:41]
	s_xor_b64 s[42:43], exec, s[42:43]
	s_cbranch_execz .LBB0_451
	v_mov_b32_e32 v32, v103
.LBB0_451:
	s_andn2_saveexec_b64 s[42:43], s[42:43]
	s_cbranch_execz .LBB0_453
	v_mov_b32_e32 v32, v103
	s_waitcnt vmcnt(0)
	v_fmac_f32_e32 v28, v20, v32
.LBB0_453:
	s_or_b64 exec, exec, s[42:43]
	ds_read_b32 v31, v30 offset:8
	s_waitcnt vmcnt(0)
	v_fma_f32 v32, v23, v32, v0
	s_and_saveexec_b64 s[42:43], vcc
	v_fmac_f32_e32 v32, v22, v33
	s_or_b64 exec, exec, s[42:43]
	v_or_b32_e32 v33, 3, v10
	s_movk_i32 s4, 0xff
	v_cmp_gt_i32_e64 s[42:43], s4, v33
	s_and_saveexec_b64 s[44:45], s[42:43]
	s_cbranch_execz .LBB0_457
	v_mov_b32_e32 v33, v104
	s_waitcnt vmcnt(0)
	v_fmac_f32_e32 v32, v20, v33
.LBB0_457:
	s_or_b64 exec, exec, s[44:45]
	v_mov_b32_e32 v37, v105
	ds_read_b32 v33, v30 offset:12
	s_waitcnt vmcnt(0)
	v_fma_f32 v34, v23, v37, v0
	s_and_saveexec_b64 s[44:45], vcc
	s_cbranch_execz .LBB0_459
	v_mov_b32_e32 v35, v106
	s_waitcnt vmcnt(0)
	v_fmac_f32_e32 v34, v22, v35
.LBB0_459:
	s_or_b64 exec, exec, s[44:45]
	v_or_b32_e32 v35, 16, v10
	s_movk_i32 s4, 0xfe
	v_cmp_lt_i32_e64 s[44:45], s4, v35
	s_and_saveexec_b64 s[46:47], s[44:45]
	s_xor_b64 s[46:47], exec, s[46:47]
	s_cbranch_execz .LBB0_461
	v_mov_b32_e32 v38, v107
.LBB0_461:
	s_andn2_saveexec_b64 s[46:47], s[46:47]
	s_cbranch_execz .LBB0_463
	v_mov_b32_e32 v38, v107
	s_waitcnt vmcnt(0)
	v_fmac_f32_e32 v34, v20, v38
.LBB0_463:
	s_or_b64 exec, exec, s[46:47]
	ds_read_b32 v35, v30 offset:64
	s_waitcnt vmcnt(0)
	v_fma_f32 v36, v23, v38, v0
	s_and_saveexec_b64 s[46:47], vcc
	v_fmac_f32_e32 v36, v22, v37
	s_or_b64 exec, exec, s[46:47]
	v_or_b32_e32 v37, 17, v10
	v_cmp_lt_i32_e64 s[46:47], s4, v37
	s_and_saveexec_b64 s[48:49], s[46:47]
	s_xor_b64 s[48:49], exec, s[48:49]
	s_cbranch_execz .LBB0_467
	v_mov_b32_e32 v37, v108
.LBB0_467:
	s_andn2_saveexec_b64 s[48:49], s[48:49]
	s_cbranch_execz .LBB0_469
	v_mov_b32_e32 v37, v108
	s_waitcnt vmcnt(0)
	v_fmac_f32_e32 v36, v20, v37
.LBB0_469:
	s_or_b64 exec, exec, s[48:49]
	ds_read_b32 v39, v30 offset:68
	s_waitcnt vmcnt(0)
	v_fma_f32 v40, v23, v37, v0
	s_and_saveexec_b64 s[48:49], vcc
	v_fmac_f32_e32 v40, v22, v38
	s_or_b64 exec, exec, s[48:49]
	v_or_b32_e32 v38, 18, v10
	v_cmp_lt_i32_e64 s[48:49], s4, v38
	s_and_saveexec_b64 s[50:51], s[48:49]
	s_xor_b64 s[50:51], exec, s[50:51]
	s_cbranch_execz .LBB0_473
	v_mov_b32_e32 v41, v109
.LBB0_473:
	s_andn2_saveexec_b64 s[50:51], s[50:51]
	s_cbranch_execz .LBB0_475
	v_mov_b32_e32 v41, v109
	s_waitcnt vmcnt(0)
	v_fmac_f32_e32 v40, v20, v41
.LBB0_475:
	s_or_b64 exec, exec, s[50:51]
	ds_read_b32 v38, v30 offset:72
	s_waitcnt vmcnt(0)
	v_fmac_f32_e32 v0, v23, v41
	s_and_saveexec_b64 s[50:51], vcc
	v_fmac_f32_e32 v0, v22, v37
	s_or_b64 exec, exec, s[50:51]
	v_or_b32_e32 v22, 19, v10
	s_movk_i32 s4, 0xff
	v_cmp_gt_i32_e64 s[50:51], s4, v22
	s_and_saveexec_b64 s[56:57], s[50:51]
	s_cbranch_execz .LBB0_479
	v_mov_b32_e32 v14, v110
	s_waitcnt vmcnt(0)
	v_fmac_f32_e32 v0, v20, v14
.LBB0_479:
	s_or_b64 exec, exec, s[56:57]
	ds_read_b32 v14, v30 offset:76
	s_waitcnt lgkmcnt(4)
	v_fma_f32 v5, v21, v33, v5
	v_fma_f32 v4, v21, v31, v4
	v_fma_f32 v3, v21, v24, v3
	v_fmac_f32_e32 v2, v21, v26
	s_waitcnt lgkmcnt(1)
	v_fma_f32 v8, v21, v38, v8
	v_fma_f32 v7, v21, v39, v7
	v_fma_f32 v6, v21, v35, v6
	v_mul_f32_e32 v5, v32, v5
	v_mul_f32_e32 v4, v28, v4
	v_mul_f32_e32 v3, v27, v3
	v_mul_f32_e32 v2, v25, v2
	s_waitcnt lgkmcnt(0)
	v_fmac_f32_e32 v9, v21, v14
	v_mul_f32_e32 v8, v40, v8
	v_mul_f32_e32 v7, v36, v7
	v_mul_f32_e32 v6, v34, v6
	s_barrier
	v_mul_f32_e32 v9, v0, v9
	ds_write_b128 v30, v[2:5]
	v_cvt_pk_bf16_f32 v2, v2, v3
	v_cvt_pk_bf16_f32 v3, v4, v5
	v_lshl_add_u32 v0, v10, 1, v19
	ds_write_b64 v0, v[2:3] offset:20480
	ds_write_b128 v30, v[6:9] offset:64
	v_cvt_pk_bf16_f32 v2, v6, v7
	v_cvt_pk_bf16_f32 v3, v8, v9
	ds_write_b64 v0, v[2:3] offset:20512
	s_waitcnt lgkmcnt(0)
	s_barrier
	ds_read_b128 v[2:5], v17 offset:37856
	ds_read_b128 v[6:9], v18 offset:20480
	ds_read_b128 v[20:23], v17 offset:37920
	ds_read_b128 v[24:27], v18 offset:20544
	s_waitcnt lgkmcnt(2)
	v_mfma_f32_16x16x32_bf16 v[2:5], v[2:5], v[6:9], 0
	ds_read_b128 v[32:35], v17 offset:37984
	ds_read_b128 v[36:39], v18 offset:20608
	s_or_b32 s26, s74, 0x200
	s_add_u32 s56, s24, 0x800
	s_waitcnt lgkmcnt(2)
	v_mfma_f32_16x16x32_bf16 v[2:5], v[20:23], v[24:27], v[2:5]
	ds_read_b128 v[20:23], v17 offset:38048
	ds_read_b128 v[40:43], v18 offset:20672
	s_addc_u32 s57, s25, 0
	s_waitcnt lgkmcnt(2)
	v_mfma_f32_16x16x32_bf16 v[2:5], v[32:35], v[36:39], v[2:5]
	ds_read_b128 v[32:35], v17 offset:38112
	ds_read_b128 v[44:47], v18 offset:20736
	s_waitcnt lgkmcnt(2)
	v_mfma_f32_16x16x32_bf16 v[2:5], v[20:23], v[40:43], v[2:5]
	ds_read_b128 v[20:23], v17 offset:38176
	ds_read_b128 v[48:51], v18 offset:20800
	s_waitcnt lgkmcnt(2)
	v_mfma_f32_16x16x32_bf16 v[2:5], v[32:35], v[44:47], v[2:5]
	ds_read_b128 v[32:35], v17 offset:38240
	ds_read_b128 v[52:55], v18 offset:20864
	ds_read_b128 v[56:59], v18 offset:20928
	s_waitcnt lgkmcnt(3)
	v_mfma_f32_16x16x32_bf16 v[2:5], v[20:23], v[48:51], v[2:5]
	ds_read_b128 v[20:23], v17 offset:38304
	s_waitcnt lgkmcnt(2)
	v_mfma_f32_16x16x32_bf16 v[2:5], v[32:35], v[52:55], v[2:5]
	s_waitcnt lgkmcnt(0)
	v_mfma_f32_16x16x32_bf16 v[2:5], v[20:23], v[56:59], v[2:5]
	ds_read_b128 v[18:21], v16 offset:37856
	global_load_dword v32, v1, s[24:25] offset:2048
	global_load_dword v33, v1, s[56:57] offset:3072
	global_load_dword v31, v203, s[24:25]
	global_load_dword v15, v1, s[52:53] offset:2048
	v_mad_u64_u32 v[12:13], s[24:25], s26, v215, v[12:13]
	v_lshl_add_u64 v[12:13], v[10:11], 2, v[12:13]
	global_load_dword v14, v[12:13], off
	global_load_dword v112, v[12:13], off offset:-4
	global_load_dword v113, v[12:13], off offset:4
	global_load_dword v114, v[12:13], off offset:8
	global_load_dword v115, v[12:13], off offset:12
	global_load_dword v116, v[12:13], off offset:16
	global_load_dword v118, v[12:13], off offset:60
	global_load_dword v117, v[12:13], off offset:64
	global_load_dword v119, v[12:13], off offset:68
	global_load_dword v120, v[12:13], off offset:72
	global_load_dword v121, v[12:13], off offset:76
	global_load_dword v122, v[12:13], off offset:80
	global_load_dword v0, v1, s[54:55] offset:-2048
	s_waitcnt lgkmcnt(0)
	v_mfma_f32_16x16x32_bf16 v[6:9], v[18:21], v[6:9], 0
	ds_read_b128 v[18:21], v16 offset:37920
	s_waitcnt lgkmcnt(0)
	v_mfma_f32_16x16x32_bf16 v[6:9], v[18:21], v[24:27], v[6:9]
	ds_read_b128 v[18:21], v16 offset:37984
	s_waitcnt lgkmcnt(0)
	v_mfma_f32_16x16x32_bf16 v[6:9], v[18:21], v[36:39], v[6:9]
	ds_read_b128 v[18:21], v16 offset:38048
	s_waitcnt lgkmcnt(0)
	v_mfma_f32_16x16x32_bf16 v[6:9], v[18:21], v[40:43], v[6:9]
	ds_read_b128 v[18:21], v16 offset:38112
	s_waitcnt lgkmcnt(0)
	v_mfma_f32_16x16x32_bf16 v[6:9], v[18:21], v[44:47], v[6:9]
	ds_read_b128 v[18:21], v16 offset:38176
	s_waitcnt lgkmcnt(0)
	v_mfma_f32_16x16x32_bf16 v[6:9], v[18:21], v[48:51], v[6:9]
	ds_read_b128 v[18:21], v16 offset:38240
	s_waitcnt lgkmcnt(0)
	v_mfma_f32_16x16x32_bf16 v[6:9], v[18:21], v[52:55], v[6:9]
	ds_read_b128 v[16:19], v16 offset:38304
	s_waitcnt lgkmcnt(0)
	v_mfma_f32_16x16x32_bf16 v[6:9], v[16:19], v[56:59], v[6:9]
	s_waitcnt vmcnt(1)
	v_fma_f32 v16, v33, v14, v15
	s_and_saveexec_b64 s[24:25], s[0:1]
	s_cbranch_execz .LBB0_481
	v_mov_b32_e32 v17, v112
	s_waitcnt vmcnt(0)
	v_fmac_f32_e32 v16, v32, v17
.LBB0_481:
	s_or_b64 exec, exec, s[24:25]
	s_and_saveexec_b64 s[0:1], s[36:37]
	s_xor_b64 s[0:1], exec, s[0:1]
	s_cbranch_execz .LBB0_483
	v_mov_b32_e32 v21, v113
	s_andn2_saveexec_b64 s[0:1], s[0:1]
	s_cbranch_execnz .LBB0_484
	s_branch .LBB0_485

.LBB0_484:
	v_mov_b32_e32 v21, v113
	s_waitcnt vmcnt(0)
	v_fmac_f32_e32 v16, v31, v21
.LBB0_485:
	s_or_b64 exec, exec, s[0:1]
	ds_read_b32 v18, v30
	s_waitcnt vmcnt(0)
	v_fma_f32 v17, v33, v21, v15
	s_and_saveexec_b64 s[0:1], vcc
	v_fmac_f32_e32 v17, v32, v14
	s_or_b64 exec, exec, s[0:1]
	s_and_saveexec_b64 s[0:1], s[38:39]
	s_xor_b64 s[0:1], exec, s[0:1]
	s_cbranch_execz .LBB0_489
	v_mov_b32_e32 v14, v114
	s_andn2_saveexec_b64 s[0:1], s[0:1]
	s_cbranch_execnz .LBB0_490
	s_branch .LBB0_491

.LBB0_490:
	v_mov_b32_e32 v14, v114
	s_waitcnt vmcnt(0)
	v_fmac_f32_e32 v17, v31, v14
.LBB0_491:
	s_or_b64 exec, exec, s[0:1]
	ds_read_b32 v19, v30 offset:4
	s_waitcnt vmcnt(0)
	v_fma_f32 v20, v33, v14, v15
	s_and_saveexec_b64 s[0:1], vcc
	v_fmac_f32_e32 v20, v32, v21
	s_or_b64 exec, exec, s[0:1]
	s_and_saveexec_b64 s[0:1], s[40:41]
	s_xor_b64 s[0:1], exec, s[0:1]
	s_cbranch_execz .LBB0_495
	v_mov_b32_e32 v21, v115
	s_andn2_saveexec_b64 s[0:1], s[0:1]
	s_cbranch_execnz .LBB0_496
	s_branch .LBB0_497

.LBB0_496:
	v_mov_b32_e32 v21, v115
	s_waitcnt vmcnt(0)
	v_fmac_f32_e32 v20, v31, v21
.LBB0_497:
	s_or_b64 exec, exec, s[0:1]
	ds_read_b32 v22, v30 offset:8
	s_waitcnt vmcnt(0)
	v_fma_f32 v21, v33, v21, v15
	s_and_saveexec_b64 s[0:1], vcc
	v_fmac_f32_e32 v21, v32, v14
	s_or_b64 exec, exec, s[0:1]
	s_and_saveexec_b64 s[0:1], s[42:43]
	s_cbranch_execz .LBB0_501
	v_mov_b32_e32 v14, v116
	s_waitcnt vmcnt(0)
	v_fmac_f32_e32 v21, v31, v14
.LBB0_501:
	s_or_b64 exec, exec, s[0:1]
	v_mov_b32_e32 v14, v117
	ds_read_b32 v23, v30 offset:12
	s_waitcnt vmcnt(0)
	v_fma_f32 v24, v33, v14, v15
	s_and_saveexec_b64 s[0:1], vcc
	s_cbranch_execz .LBB0_503
	v_mov_b32_e32 v25, v118
	s_waitcnt vmcnt(0)
	v_fmac_f32_e32 v24, v32, v25
.LBB0_503:
	s_or_b64 exec, exec, s[0:1]
	s_and_saveexec_b64 s[0:1], s[44:45]
	s_xor_b64 s[0:1], exec, s[0:1]
	s_cbranch_execz .LBB0_505
	v_mov_b32_e32 v28, v119
	s_andn2_saveexec_b64 s[0:1], s[0:1]
	s_cbranch_execnz .LBB0_506
	s_branch .LBB0_507

.LBB0_506:
	v_mov_b32_e32 v28, v119
	s_waitcnt vmcnt(0)
	v_fmac_f32_e32 v24, v31, v28
.LBB0_507:
	s_or_b64 exec, exec, s[0:1]
	ds_read_b32 v26, v30 offset:64
	s_waitcnt vmcnt(0)
	v_fma_f32 v25, v33, v28, v15
	s_and_saveexec_b64 s[0:1], vcc
	v_fmac_f32_e32 v25, v32, v14
	s_or_b64 exec, exec, s[0:1]
	s_and_saveexec_b64 s[0:1], s[46:47]
	s_xor_b64 s[0:1], exec, s[0:1]
	s_cbranch_execz .LBB0_511
	v_mov_b32_e32 v34, v120
	s_andn2_saveexec_b64 s[0:1], s[0:1]
	s_cbranch_execnz .LBB0_512
	s_branch .LBB0_513

.LBB0_512:
	v_mov_b32_e32 v34, v120
	s_waitcnt vmcnt(0)
	v_fmac_f32_e32 v25, v31, v34
.LBB0_513:
	s_or_b64 exec, exec, s[0:1]
	ds_read_b32 v27, v30 offset:68
	s_waitcnt vmcnt(0)
	v_fma_f32 v14, v33, v34, v15
	s_and_saveexec_b64 s[0:1], vcc
	v_fmac_f32_e32 v14, v32, v28
	s_or_b64 exec, exec, s[0:1]
	s_and_saveexec_b64 s[0:1], s[48:49]
	s_xor_b64 s[0:1], exec, s[0:1]
	s_cbranch_execz .LBB0_517
	v_mov_b32_e32 v35, v121
	s_andn2_saveexec_b64 s[0:1], s[0:1]
	s_cbranch_execnz .LBB0_518
	s_branch .LBB0_519

.LBB0_518:
	v_mov_b32_e32 v35, v121
	s_waitcnt vmcnt(0)
	v_fmac_f32_e32 v14, v31, v35
.LBB0_519:
	s_or_b64 exec, exec, s[0:1]
	ds_read_b32 v28, v30 offset:72
	s_waitcnt vmcnt(0)
	v_fmac_f32_e32 v15, v33, v35
	s_and_saveexec_b64 s[0:1], vcc
	v_fmac_f32_e32 v15, v32, v34
	s_or_b64 exec, exec, s[0:1]
	s_and_saveexec_b64 s[0:1], s[50:51]
	s_cbranch_execz .LBB0_523
	v_mov_b32_e32 v12, v122
	s_waitcnt vmcnt(0)
	v_fmac_f32_e32 v15, v31, v12
